# grid barrier (in-loop sites): the last XCD leader no longer bumps the now-unused TOPGEN word, so it does not wait for that atomic's ack before releasing its XCD
# baseline (speedup 1.0000x reference)
; __device__ __forceinline__ unsigned xb_ld(unsigned* p)              { return __hip_atomic_load(p, __ATOMIC_RELAXED, __HIP_MEMORY_SCOPE_AGENT); }
; __device__ __forceinline__ unsigned xb_add(unsigned* p, unsigned v) { return __hip_atomic_fetch_add(p, v, __ATOMIC_RELAXED, __HIP_MEMORY_SCOPE_AGENT); }
; #define XB_SPIN(cond, bar) do { unsigned _sp = 0; while (cond) { \
;     if ((++_sp & 255u) == 0u) { if (xb_ld(&(bar)[XB_TMO])) break; if (_sp > XB_SPIN_CAP) { atomicAdd(&(bar)[XB_TMO], 1u); break; } } } } while (0)
; __device__ __forceinline__ void xcd_barrier(const XcdBarrier& b) {
;     ...
;         const unsigned old = xb_add(&bar[XB_XSUB(b.x)], 1u);
;         const unsigned gen = old / nloc;
;         if (old + 1u == (gen + 1u) * nloc) {
;             __builtin_amdgcn_fence(__ATOMIC_RELEASE, "agent");
;             asm volatile("s_waitcnt vmcnt(0)" ::: "memory");
;             const unsigned og = xb_add(&bar[XB_TOP], 1u);
;             const unsigned tg = og / nx;
;             if (og + 1u == (tg + 1u) * nx) xb_add(&bar[XB_TOPGEN], 1u);
;             else XB_SPIN(xb_ld(&bar[XB_TOPGEN]) == tg, bar);
.LBB0_215:
	s_or_b64 exec, exec, s[8:9]
	v_cvt_f32_u32_e32 v3, v0
	s_waitcnt vmcnt(0)
	v_readfirstlane_b32 s6, v2
	s_mov_b64 s[8:9], 0
	v_rcp_iflag_f32_e32 v3, v3
	v_add_u32_e32 v1, s6, v1
	v_add_u32_e32 v4, 1, v1
	v_readlane_b32 s6, v253, 62
	v_mul_f32_e32 v2, 0x4f7ffffe, v3
	v_cvt_u32_f32_e32 v2, v2
	v_sub_u32_e32 v3, 0, v0
	v_readlane_b32 s7, v253, 63
	v_mul_lo_u32 v3, v3, v2
	v_mul_hi_u32 v3, v2, v3
	v_add_u32_e32 v2, v2, v3
	v_mul_hi_u32 v2, v1, v2
	v_mul_lo_u32 v3, v2, v0
	v_sub_u32_e32 v1, v1, v3
	v_add_u32_e32 v5, 1, v2
	v_cmp_ge_u32_e32 vcc, v1, v0
	v_sub_u32_e32 v3, v1, v0
	s_nop 0
	v_cndmask_b32_e32 v2, v2, v5, vcc
	v_cndmask_b32_e32 v1, v1, v3, vcc
	v_add_u32_e32 v3, 1, v2
	v_cmp_ge_u32_e32 vcc, v1, v0
	s_nop 1
	v_cndmask_b32_e32 v2, v2, v3, vcc
	v_mul_lo_u32 v1, v0, v2
	v_add_u32_e32 v0, v1, v0
	v_cmp_ne_u32_e32 vcc, v4, v0
	v_mov_b32_e32 v5, v0
	v_mov_b64_e32 v[0:1], s[6:7]
	s_and_saveexec_b64 s[6:7], vcc
	s_cbranch_execz .LBB0_227
	v_readlane_b32 s8, v253, 60
	v_readlane_b32 s9, v253, 61
	s_mov_b64 s[10:11], 0
	s_nop 3
	global_load_dword v0, v161, s[8:9] sc1
	s_waitcnt vmcnt(0)
	v_cmp_lt_u32_e32 vcc, v0, v5
	s_and_saveexec_b64 s[8:9], vcc
	s_cbranch_execz .LBB0_226
	s_mov_b32 s20, 1
	s_branch .LBB0_219

; __device__ __forceinline__ unsigned xb_ld(unsigned* p)              { return __hip_atomic_load(p, __ATOMIC_RELAXED, __HIP_MEMORY_SCOPE_AGENT); }
; __device__ __forceinline__ unsigned xb_add(unsigned* p, unsigned v) { return __hip_atomic_fetch_add(p, v, __ATOMIC_RELAXED, __HIP_MEMORY_SCOPE_AGENT); }
; #define XB_SPIN(cond, bar) do { unsigned _sp = 0; while (cond) { \
;     if ((++_sp & 255u) == 0u) { if (xb_ld(&(bar)[XB_TMO])) break; if (_sp > XB_SPIN_CAP) { atomicAdd(&(bar)[XB_TMO], 1u); break; } } } } while (0)
; __device__ __forceinline__ void xcd_barrier(const XcdBarrier& b) {
;     ...
;         const unsigned old = xb_add(&bar[XB_XSUB(b.x)], 1u);
;         const unsigned gen = old / nloc;
;         if (old + 1u == (gen + 1u) * nloc) {
;             __builtin_amdgcn_fence(__ATOMIC_RELEASE, "agent");
;             asm volatile("s_waitcnt vmcnt(0)" ::: "memory");
;             const unsigned og = xb_add(&bar[XB_TOP], 1u);
;             const unsigned tg = og / nx;
;             if (og + 1u == (tg + 1u) * nx) xb_add(&bar[XB_TOPGEN], 1u);
;             else XB_SPIN(xb_ld(&bar[XB_TOPGEN]) == tg, bar);
.LBB0_651:
	s_or_b64 exec, exec, s[10:11]
	v_cvt_f32_u32_e32 v3, v0
	s_waitcnt vmcnt(0)
	v_readfirstlane_b32 s8, v2
	s_mov_b64 s[10:11], 0
	v_rcp_iflag_f32_e32 v3, v3
	v_add_u32_e32 v1, s8, v1
	v_add_u32_e32 v4, 1, v1
	v_readlane_b32 s8, v253, 62
	v_mul_f32_e32 v2, 0x4f7ffffe, v3
	v_cvt_u32_f32_e32 v2, v2
	v_sub_u32_e32 v3, 0, v0
	v_readlane_b32 s9, v253, 63
	v_mul_lo_u32 v3, v3, v2
	v_mul_hi_u32 v3, v2, v3
	v_add_u32_e32 v2, v2, v3
	v_mul_hi_u32 v2, v1, v2
	v_mul_lo_u32 v3, v2, v0
	v_sub_u32_e32 v1, v1, v3
	v_add_u32_e32 v5, 1, v2
	v_cmp_ge_u32_e32 vcc, v1, v0
	v_sub_u32_e32 v3, v1, v0
	s_nop 0
	v_cndmask_b32_e32 v2, v2, v5, vcc
	v_cndmask_b32_e32 v1, v1, v3, vcc
	v_add_u32_e32 v3, 1, v2
	v_cmp_ge_u32_e32 vcc, v1, v0
	s_nop 1
	v_cndmask_b32_e32 v2, v2, v3, vcc
	v_mul_lo_u32 v1, v0, v2
	v_add_u32_e32 v0, v1, v0
	v_cmp_ne_u32_e32 vcc, v4, v0
	v_mov_b32_e32 v5, v0
	v_mov_b64_e32 v[0:1], s[8:9]
	s_and_saveexec_b64 s[8:9], vcc
	s_cbranch_execz .LBB0_663
	v_readlane_b32 s10, v253, 60
	v_readlane_b32 s11, v253, 61
	s_mov_b64 s[12:13], 0
	s_nop 3
	global_load_dword v0, v161, s[10:11] sc1
	s_waitcnt vmcnt(0)
	v_cmp_lt_u32_e32 vcc, v0, v5
	s_and_saveexec_b64 s[10:11], vcc
	s_cbranch_execz .LBB0_662
	s_mov_b32 s20, 1
	s_branch .LBB0_655

; __device__ __forceinline__ unsigned xb_ld(unsigned* p)              { return __hip_atomic_load(p, __ATOMIC_RELAXED, __HIP_MEMORY_SCOPE_AGENT); }
; __device__ __forceinline__ unsigned xb_add(unsigned* p, unsigned v) { return __hip_atomic_fetch_add(p, v, __ATOMIC_RELAXED, __HIP_MEMORY_SCOPE_AGENT); }
; #define XB_SPIN(cond, bar) do { unsigned _sp = 0; while (cond) { \
;     if ((++_sp & 255u) == 0u) { if (xb_ld(&(bar)[XB_TMO])) break; if (_sp > XB_SPIN_CAP) { atomicAdd(&(bar)[XB_TMO], 1u); break; } } } } while (0)
; __device__ __forceinline__ void xcd_barrier(const XcdBarrier& b) {
;     ...
;         const unsigned old = xb_add(&bar[XB_XSUB(b.x)], 1u);
;         const unsigned gen = old / nloc;
;         if (old + 1u == (gen + 1u) * nloc) {
;             __builtin_amdgcn_fence(__ATOMIC_RELEASE, "agent");
;             asm volatile("s_waitcnt vmcnt(0)" ::: "memory");
;             const unsigned og = xb_add(&bar[XB_TOP], 1u);
;             const unsigned tg = og / nx;
;             if (og + 1u == (tg + 1u) * nx) xb_add(&bar[XB_TOPGEN], 1u);
;             else XB_SPIN(xb_ld(&bar[XB_TOPGEN]) == tg, bar);
.LBB0_812:
	s_or_b64 exec, exec, s[10:11]
	s_waitcnt vmcnt(0)
	v_readfirstlane_b32 s8, v2
	v_cvt_f32_u32_e32 v2, v0
	v_sub_u32_e32 v3, 0, v0
	v_add_u32_e32 v1, s8, v1
	v_readlane_b32 s8, v253, 62
	v_rcp_iflag_f32_e32 v2, v2
	v_readlane_b32 s9, v253, 63
	s_mov_b64 s[10:11], 0
	v_mul_f32_e32 v2, 0x4f7ffffe, v2
	v_cvt_u32_f32_e32 v2, v2
	v_mul_lo_u32 v3, v3, v2
	v_mul_hi_u32 v3, v2, v3
	v_add_u32_e32 v2, v2, v3
	v_mul_hi_u32 v2, v1, v2
	v_mul_lo_u32 v3, v2, v0
	v_sub_u32_e32 v3, v1, v3
	v_cmp_ge_u32_e32 vcc, v3, v0
	v_add_u32_e32 v4, 1, v2
	v_add_u32_e32 v1, 1, v1
	v_cndmask_b32_e32 v2, v2, v4, vcc
	v_sub_u32_e32 v4, v3, v0
	v_cndmask_b32_e32 v3, v3, v4, vcc
	v_cmp_ge_u32_e32 vcc, v3, v0
	v_add_u32_e32 v3, 1, v2
	s_nop 0
	v_cndmask_b32_e32 v2, v2, v3, vcc
	v_mul_lo_u32 v3, v0, v2
	v_add_u32_e32 v0, v3, v0
	v_cmp_ne_u32_e32 vcc, v1, v0
	v_mov_b32_e32 v5, v0
	v_mov_b64_e32 v[0:1], s[8:9]
	s_and_saveexec_b64 s[8:9], vcc
	s_cbranch_execz .LBB0_824
	v_readlane_b32 s10, v253, 60
	v_readlane_b32 s11, v253, 61
	s_mov_b64 s[12:13], 0
	s_nop 3
	global_load_dword v0, v161, s[10:11] sc1
	s_waitcnt vmcnt(0)
	v_cmp_lt_u32_e32 vcc, v0, v5
	s_and_saveexec_b64 s[10:11], vcc
	s_cbranch_execz .LBB0_823
	s_mov_b32 s20, 1
	s_branch .LBB0_816

; __device__ __forceinline__ unsigned xb_ld(unsigned* p)              { return __hip_atomic_load(p, __ATOMIC_RELAXED, __HIP_MEMORY_SCOPE_AGENT); }
; __device__ __forceinline__ unsigned xb_add(unsigned* p, unsigned v) { return __hip_atomic_fetch_add(p, v, __ATOMIC_RELAXED, __HIP_MEMORY_SCOPE_AGENT); }
; #define XB_SPIN(cond, bar) do { unsigned _sp = 0; while (cond) { \
;     if ((++_sp & 255u) == 0u) { if (xb_ld(&(bar)[XB_TMO])) break; if (_sp > XB_SPIN_CAP) { atomicAdd(&(bar)[XB_TMO], 1u); break; } } } } while (0)
; __device__ __forceinline__ void xcd_barrier(const XcdBarrier& b) {
;     ...
;         const unsigned old = xb_add(&bar[XB_XSUB(b.x)], 1u);
;         const unsigned gen = old / nloc;
;         if (old + 1u == (gen + 1u) * nloc) {
;             __builtin_amdgcn_fence(__ATOMIC_RELEASE, "agent");
;             asm volatile("s_waitcnt vmcnt(0)" ::: "memory");
;             const unsigned og = xb_add(&bar[XB_TOP], 1u);
;             const unsigned tg = og / nx;
;             if (og + 1u == (tg + 1u) * nx) xb_add(&bar[XB_TOPGEN], 1u);
;             else XB_SPIN(xb_ld(&bar[XB_TOPGEN]) == tg, bar);
.LBB0_893:
	s_or_b64 exec, exec, s[8:9]
	s_waitcnt vmcnt(0)
	v_readfirstlane_b32 s6, v2
	v_cvt_f32_u32_e32 v2, v0
	v_sub_u32_e32 v3, 0, v0
	v_add_u32_e32 v1, s6, v1
	v_readlane_b32 s6, v253, 62
	v_rcp_iflag_f32_e32 v2, v2
	v_readlane_b32 s7, v253, 63
	s_mov_b64 s[8:9], 0
	v_mul_f32_e32 v2, 0x4f7ffffe, v2
	v_cvt_u32_f32_e32 v2, v2
	v_mul_lo_u32 v3, v3, v2
	v_mul_hi_u32 v3, v2, v3
	v_add_u32_e32 v2, v2, v3
	v_mul_hi_u32 v2, v1, v2
	v_mul_lo_u32 v3, v2, v0
	v_sub_u32_e32 v3, v1, v3
	v_cmp_ge_u32_e32 vcc, v3, v0
	v_add_u32_e32 v4, 1, v2
	v_add_u32_e32 v1, 1, v1
	v_cndmask_b32_e32 v2, v2, v4, vcc
	v_sub_u32_e32 v4, v3, v0
	v_cndmask_b32_e32 v3, v3, v4, vcc
	v_cmp_ge_u32_e32 vcc, v3, v0
	v_add_u32_e32 v3, 1, v2
	s_nop 0
	v_cndmask_b32_e32 v2, v2, v3, vcc
	v_mul_lo_u32 v3, v0, v2
	v_add_u32_e32 v0, v3, v0
	v_cmp_ne_u32_e32 vcc, v1, v0
	v_mov_b32_e32 v5, v0
	v_mov_b64_e32 v[0:1], s[6:7]
	s_and_saveexec_b64 s[6:7], vcc
	s_cbranch_execz .LBB0_905
	v_readlane_b32 s8, v253, 60
	v_readlane_b32 s9, v253, 61
	s_mov_b64 s[10:11], 0
	s_nop 3
	global_load_dword v0, v161, s[8:9] sc1
	s_waitcnt vmcnt(0)
	v_cmp_lt_u32_e32 vcc, v0, v5
	s_and_saveexec_b64 s[8:9], vcc
	s_cbranch_execz .LBB0_904
	s_mov_b32 s15, 1
	s_branch .LBB0_897

; __device__ __forceinline__ unsigned xb_ld(unsigned* p)              { return __hip_atomic_load(p, __ATOMIC_RELAXED, __HIP_MEMORY_SCOPE_AGENT); }
; __device__ __forceinline__ unsigned xb_add(unsigned* p, unsigned v) { return __hip_atomic_fetch_add(p, v, __ATOMIC_RELAXED, __HIP_MEMORY_SCOPE_AGENT); }
; #define XB_SPIN(cond, bar) do { unsigned _sp = 0; while (cond) { \
;     if ((++_sp & 255u) == 0u) { if (xb_ld(&(bar)[XB_TMO])) break; if (_sp > XB_SPIN_CAP) { atomicAdd(&(bar)[XB_TMO], 1u); break; } } } } while (0)
; __device__ __forceinline__ void xcd_barrier(const XcdBarrier& b) {
;     ...
;         const unsigned old = xb_add(&bar[XB_XSUB(b.x)], 1u);
;         const unsigned gen = old / nloc;
;         if (old + 1u == (gen + 1u) * nloc) {
;             __builtin_amdgcn_fence(__ATOMIC_RELEASE, "agent");
;             asm volatile("s_waitcnt vmcnt(0)" ::: "memory");
;             const unsigned og = xb_add(&bar[XB_TOP], 1u);
;             const unsigned tg = og / nx;
;             if (og + 1u == (tg + 1u) * nx) xb_add(&bar[XB_TOPGEN], 1u);
;             else XB_SPIN(xb_ld(&bar[XB_TOPGEN]) == tg, bar);
.LBB0_1117:
	s_or_b64 exec, exec, s[8:9]
	s_waitcnt vmcnt(0)
	v_readfirstlane_b32 s6, v2
	v_cvt_f32_u32_e32 v2, v0
	v_sub_u32_e32 v3, 0, v0
	v_add_u32_e32 v1, s6, v1
	v_readlane_b32 s6, v253, 62
	v_rcp_iflag_f32_e32 v2, v2
	v_readlane_b32 s7, v253, 63
	s_mov_b64 s[8:9], 0
	v_mul_f32_e32 v2, 0x4f7ffffe, v2
	v_cvt_u32_f32_e32 v2, v2
	v_mul_lo_u32 v3, v3, v2
	v_mul_hi_u32 v3, v2, v3
	v_add_u32_e32 v2, v2, v3
	v_mul_hi_u32 v2, v1, v2
	v_mul_lo_u32 v3, v2, v0
	v_sub_u32_e32 v3, v1, v3
	v_cmp_ge_u32_e32 vcc, v3, v0
	v_add_u32_e32 v4, 1, v2
	v_add_u32_e32 v1, 1, v1
	v_cndmask_b32_e32 v2, v2, v4, vcc
	v_sub_u32_e32 v4, v3, v0
	v_cndmask_b32_e32 v3, v3, v4, vcc
	v_cmp_ge_u32_e32 vcc, v3, v0
	v_add_u32_e32 v3, 1, v2
	s_nop 0
	v_cndmask_b32_e32 v2, v2, v3, vcc
	v_mul_lo_u32 v3, v0, v2
	v_add_u32_e32 v0, v3, v0
	v_cmp_ne_u32_e32 vcc, v1, v0
	v_mov_b32_e32 v5, v0
	v_mov_b64_e32 v[0:1], s[6:7]
	s_and_saveexec_b64 s[6:7], vcc
	s_cbranch_execz .LBB0_1129
	v_readlane_b32 s8, v253, 60
	v_readlane_b32 s9, v253, 61
	s_mov_b64 s[10:11], 0
	s_nop 3
	global_load_dword v0, v161, s[8:9] sc1
	s_waitcnt vmcnt(0)
	v_cmp_lt_u32_e32 vcc, v0, v5
	s_and_saveexec_b64 s[8:9], vcc
	s_cbranch_execz .LBB0_1128
	s_mov_b64 s[38:39], s[34:35]
	s_mov_b32 s15, 1
	s_branch .LBB0_1121

; __device__ __forceinline__ unsigned xb_ld(unsigned* p)              { return __hip_atomic_load(p, __ATOMIC_RELAXED, __HIP_MEMORY_SCOPE_AGENT); }
; __device__ __forceinline__ unsigned xb_add(unsigned* p, unsigned v) { return __hip_atomic_fetch_add(p, v, __ATOMIC_RELAXED, __HIP_MEMORY_SCOPE_AGENT); }
; #define XB_SPIN(cond, bar) do { unsigned _sp = 0; while (cond) { \
;     if ((++_sp & 255u) == 0u) { if (xb_ld(&(bar)[XB_TMO])) break; if (_sp > XB_SPIN_CAP) { atomicAdd(&(bar)[XB_TMO], 1u); break; } } } } while (0)
; __device__ __forceinline__ void xcd_barrier(const XcdBarrier& b) {
;     ...
;         const unsigned old = xb_add(&bar[XB_XSUB(b.x)], 1u);
;         const unsigned gen = old / nloc;
;         if (old + 1u == (gen + 1u) * nloc) {
;             __builtin_amdgcn_fence(__ATOMIC_RELEASE, "agent");
;             asm volatile("s_waitcnt vmcnt(0)" ::: "memory");
;             const unsigned og = xb_add(&bar[XB_TOP], 1u);
;             const unsigned tg = og / nx;
;             if (og + 1u == (tg + 1u) * nx) xb_add(&bar[XB_TOPGEN], 1u);
;             else XB_SPIN(xb_ld(&bar[XB_TOPGEN]) == tg, bar);
.LBB0_1177:
	s_or_b64 exec, exec, s[10:11]
	s_waitcnt vmcnt(0)
	v_readfirstlane_b32 s8, v2
	v_cvt_f32_u32_e32 v2, v0
	v_sub_u32_e32 v3, 0, v0
	v_add_u32_e32 v1, s8, v1
	v_readlane_b32 s8, v253, 62
	v_rcp_iflag_f32_e32 v2, v2
	v_readlane_b32 s9, v253, 63
	s_mov_b64 s[10:11], 0
	v_mul_f32_e32 v2, 0x4f7ffffe, v2
	v_cvt_u32_f32_e32 v2, v2
	v_mul_lo_u32 v3, v3, v2
	v_mul_hi_u32 v3, v2, v3
	v_add_u32_e32 v2, v2, v3
	v_mul_hi_u32 v2, v1, v2
	v_mul_lo_u32 v3, v2, v0
	v_sub_u32_e32 v3, v1, v3
	v_cmp_ge_u32_e32 vcc, v3, v0
	v_add_u32_e32 v4, 1, v2
	v_add_u32_e32 v1, 1, v1
	v_cndmask_b32_e32 v2, v2, v4, vcc
	v_sub_u32_e32 v4, v3, v0
	v_cndmask_b32_e32 v3, v3, v4, vcc
	v_cmp_ge_u32_e32 vcc, v3, v0
	v_add_u32_e32 v3, 1, v2
	s_nop 0
	v_cndmask_b32_e32 v2, v2, v3, vcc
	v_mul_lo_u32 v3, v0, v2
	v_add_u32_e32 v0, v3, v0
	v_cmp_ne_u32_e32 vcc, v1, v0
	v_mov_b32_e32 v5, v0
	v_mov_b64_e32 v[0:1], s[8:9]
	s_and_saveexec_b64 s[8:9], vcc
	s_cbranch_execz .LBB0_1189
	v_readlane_b32 s10, v253, 60
	v_readlane_b32 s11, v253, 61
	s_mov_b64 s[12:13], 0
	s_nop 3
	global_load_dword v0, v161, s[10:11] sc1
	s_waitcnt vmcnt(0)
	v_cmp_lt_u32_e32 vcc, v0, v5
	s_and_saveexec_b64 s[10:11], vcc
	s_cbranch_execz .LBB0_1188
	s_mov_b32 s15, 1
	s_branch .LBB0_1181

; __device__ __forceinline__ unsigned xb_ld(unsigned* p)              { return __hip_atomic_load(p, __ATOMIC_RELAXED, __HIP_MEMORY_SCOPE_AGENT); }
; __device__ __forceinline__ unsigned xb_add(unsigned* p, unsigned v) { return __hip_atomic_fetch_add(p, v, __ATOMIC_RELAXED, __HIP_MEMORY_SCOPE_AGENT); }
; #define XB_SPIN(cond, bar) do { unsigned _sp = 0; while (cond) { \
;     if ((++_sp & 255u) == 0u) { if (xb_ld(&(bar)[XB_TMO])) break; if (_sp > XB_SPIN_CAP) { atomicAdd(&(bar)[XB_TMO], 1u); break; } } } } while (0)
; __device__ __forceinline__ void xcd_barrier(const XcdBarrier& b) {
;     ...
;         const unsigned old = xb_add(&bar[XB_XSUB(b.x)], 1u);
;         const unsigned gen = old / nloc;
;         if (old + 1u == (gen + 1u) * nloc) {
;             __builtin_amdgcn_fence(__ATOMIC_RELEASE, "agent");
;             asm volatile("s_waitcnt vmcnt(0)" ::: "memory");
;             const unsigned og = xb_add(&bar[XB_TOP], 1u);
;             const unsigned tg = og / nx;
;             if (og + 1u == (tg + 1u) * nx) xb_add(&bar[XB_TOPGEN], 1u);
;             else XB_SPIN(xb_ld(&bar[XB_TOPGEN]) == tg, bar);
.LBB0_1246:
	s_or_b64 exec, exec, s[12:13]
	s_waitcnt vmcnt(0)
	v_readfirstlane_b32 s10, v2
	v_cvt_f32_u32_e32 v2, v0
	v_sub_u32_e32 v3, 0, v0
	v_add_u32_e32 v1, s10, v1
	v_readlane_b32 s10, v253, 62
	v_rcp_iflag_f32_e32 v2, v2
	v_readlane_b32 s11, v253, 63
	s_mov_b64 s[12:13], 0
	v_mul_f32_e32 v2, 0x4f7ffffe, v2
	v_cvt_u32_f32_e32 v2, v2
	v_mul_lo_u32 v3, v3, v2
	v_mul_hi_u32 v3, v2, v3
	v_add_u32_e32 v2, v2, v3
	v_mul_hi_u32 v2, v1, v2
	v_mul_lo_u32 v3, v2, v0
	v_sub_u32_e32 v3, v1, v3
	v_cmp_ge_u32_e32 vcc, v3, v0
	v_add_u32_e32 v4, 1, v2
	v_add_u32_e32 v1, 1, v1
	v_cndmask_b32_e32 v2, v2, v4, vcc
	v_sub_u32_e32 v4, v3, v0
	v_cndmask_b32_e32 v3, v3, v4, vcc
	v_cmp_ge_u32_e32 vcc, v3, v0
	v_add_u32_e32 v3, 1, v2
	s_nop 0
	v_cndmask_b32_e32 v2, v2, v3, vcc
	v_mul_lo_u32 v3, v0, v2
	v_add_u32_e32 v0, v3, v0
	v_cmp_ne_u32_e32 vcc, v1, v0
	v_mov_b32_e32 v5, v0
	v_mov_b64_e32 v[0:1], s[10:11]
	s_and_saveexec_b64 s[10:11], vcc
	s_cbranch_execz .LBB0_1258
	v_readlane_b32 s12, v253, 60
	v_readlane_b32 s13, v253, 61
	s_mov_b64 s[34:35], 0
	s_nop 3
	global_load_dword v0, v161, s[12:13] sc1
	s_waitcnt vmcnt(0)
	v_cmp_lt_u32_e32 vcc, v0, v5
	s_and_saveexec_b64 s[12:13], vcc
	s_cbranch_execz .LBB0_1257
	s_mov_b32 s15, 1
	s_branch .LBB0_1250

; __device__ __forceinline__ unsigned xb_ld(unsigned* p)              { return __hip_atomic_load(p, __ATOMIC_RELAXED, __HIP_MEMORY_SCOPE_AGENT); }
; __device__ __forceinline__ unsigned xb_add(unsigned* p, unsigned v) { return __hip_atomic_fetch_add(p, v, __ATOMIC_RELAXED, __HIP_MEMORY_SCOPE_AGENT); }
; #define XB_SPIN(cond, bar) do { unsigned _sp = 0; while (cond) { \
;     if ((++_sp & 255u) == 0u) { if (xb_ld(&(bar)[XB_TMO])) break; if (_sp > XB_SPIN_CAP) { atomicAdd(&(bar)[XB_TMO], 1u); break; } } } } while (0)
; __device__ __forceinline__ void xcd_barrier(const XcdBarrier& b) {
;     ...
;         const unsigned old = xb_add(&bar[XB_XSUB(b.x)], 1u);
;         const unsigned gen = old / nloc;
;         if (old + 1u == (gen + 1u) * nloc) {
;             __builtin_amdgcn_fence(__ATOMIC_RELEASE, "agent");
;             asm volatile("s_waitcnt vmcnt(0)" ::: "memory");
;             const unsigned og = xb_add(&bar[XB_TOP], 1u);
;             const unsigned tg = og / nx;
;             if (og + 1u == (tg + 1u) * nx) xb_add(&bar[XB_TOPGEN], 1u);
;             else XB_SPIN(xb_ld(&bar[XB_TOPGEN]) == tg, bar);
.LBB0_1480:
	s_or_b64 exec, exec, s[8:9]
	s_waitcnt vmcnt(0)
	v_readfirstlane_b32 s6, v2
	v_cvt_f32_u32_e32 v2, v0
	v_sub_u32_e32 v3, 0, v0
	v_add_u32_e32 v1, s6, v1
	v_readlane_b32 s6, v253, 62
	v_rcp_iflag_f32_e32 v2, v2
	v_readlane_b32 s7, v253, 63
	s_mov_b64 s[8:9], 0
	v_mul_f32_e32 v2, 0x4f7ffffe, v2
	v_cvt_u32_f32_e32 v2, v2
	v_mul_lo_u32 v3, v3, v2
	v_mul_hi_u32 v3, v2, v3
	v_add_u32_e32 v2, v2, v3
	v_mul_hi_u32 v2, v1, v2
	v_mul_lo_u32 v3, v2, v0
	v_sub_u32_e32 v3, v1, v3
	v_cmp_ge_u32_e32 vcc, v3, v0
	v_add_u32_e32 v4, 1, v2
	v_add_u32_e32 v1, 1, v1
	v_cndmask_b32_e32 v2, v2, v4, vcc
	v_sub_u32_e32 v4, v3, v0
	v_cndmask_b32_e32 v3, v3, v4, vcc
	v_cmp_ge_u32_e32 vcc, v3, v0
	v_add_u32_e32 v3, 1, v2
	s_nop 0
	v_cndmask_b32_e32 v2, v2, v3, vcc
	v_mul_lo_u32 v3, v0, v2
	v_add_u32_e32 v0, v3, v0
	v_cmp_ne_u32_e32 vcc, v1, v0
	v_mov_b32_e32 v5, v0
	v_mov_b64_e32 v[0:1], s[6:7]
	s_and_saveexec_b64 s[6:7], vcc
	s_cbranch_execz .LBB0_1492
	v_readlane_b32 s8, v253, 60
	v_readlane_b32 s9, v253, 61
	s_mov_b64 s[10:11], 0
	s_nop 3
	global_load_dword v0, v161, s[8:9] sc1
	s_waitcnt vmcnt(0)
	v_cmp_lt_u32_e32 vcc, v0, v5
	s_and_saveexec_b64 s[8:9], vcc
	s_cbranch_execz .LBB0_1491
	s_mov_b32 s20, 1
	s_branch .LBB0_1484
